# adds: phase-0 gain loads hoisted, attention epilogue gate/gain loads hoisted, residual-phase gain loads hoisted (counted waits)
# baseline (speedup 1.0000x reference)
.LBB0_32:
	s_andn2_b64 vcc, exec, s[0:1]
	s_cbranch_vccnz .LBB0_50
	s_and_b32 s5, 0xffff, s5
	s_mul_i32 s0, s5, 0x3000000
	s_add_u32 s0, s44, s0
	s_addc_u32 s1, s45, 0
	s_lshl_b32 s7, s5, 13
	s_add_u32 s10, s40, s7
	s_mul_i32 s7, s4, 0xaaab
	s_addc_u32 s11, s41, 0
	s_lshr_b32 s7, s7, 20
	s_mul_i32 s28, s7, 24
	s_sub_i32 s4, s4, s28
	v_mov_b32_e32 v72, v194
	s_lshl_b32 s4, s4, 8
	v_lshlrev_b32_e32 v0, 2, v72
	v_and_b32_e32 v74, 0xfc, v0
	s_and_b32 s4, s4, 0xff00
	s_lshl_b32 s7, s7, 6
	v_ashrrev_i32_e32 v73, 6, v72
	v_or_b32_e32 v0, s4, v74
	s_and_b32 s28, s7, 0xffc0
	v_add_u32_e32 v52, s28, v73
	v_lshlrev_b32_e32 v32, 2, v0
	v_lshl_add_u64 v[0:1], s[0:1], 0, v[32:33]
	v_add_u32_e32 v4, 8, v52
	s_waitcnt lgkmcnt(0)
	v_mad_i64_i32 v[2:3], s[0:1], v52, s33, v[0:1]
	v_mad_i64_i32 v[4:5], s[0:1], v4, s33, v[0:1]
	s_barrier
	s_andn2_b64 vcc, exec, s[68:69]
	s_cbranch_vccnz .Lp0_nogain
	v_mov_b32_e32 v76, v52
	v_ashrrev_i32_e32 v77, 31, v52
	v_lshl_add_u64 v[76:77], v[76:77], 2, s[10:11]
	global_load_dword v80, v[76:77], off
	global_load_dword v82, v[76:77], off offset:32
	global_load_dword v84, v[76:77], off offset:64
	global_load_dword v86, v[76:77], off offset:96
	global_load_dword v88, v[76:77], off offset:128
	global_load_dword v90, v[76:77], off offset:160
	global_load_dword v92, v[76:77], off offset:192
	global_load_dword v94, v[76:77], off offset:224
.Lp0_nogain:
	global_load_dwordx4 v[28:31], v[2:3], off
	global_load_dwordx4 v[24:27], v[4:5], off
	v_add_u32_e32 v2, 16, v52
	v_add_u32_e32 v4, 24, v52
	v_mad_i64_i32 v[2:3], s[0:1], v2, s33, v[0:1]
	v_mad_i64_i32 v[4:5], s[0:1], v4, s33, v[0:1]
	global_load_dwordx4 v[20:23], v[2:3], off
	global_load_dwordx4 v[16:19], v[4:5], off
	v_add_u32_e32 v2, 32, v52
	v_add_u32_e32 v4, 40, v52
	v_mad_i64_i32 v[2:3], s[0:1], v2, s33, v[0:1]
	v_mad_i64_i32 v[4:5], s[0:1], v4, s33, v[0:1]
	global_load_dwordx4 v[12:15], v[2:3], off
	global_load_dwordx4 v[8:11], v[4:5], off
	v_add_u32_e32 v2, 48, v52
	v_add_u32_e32 v4, 56, v52
	v_mad_i64_i32 v[2:3], s[0:1], v2, s33, v[0:1]
	v_mad_i64_i32 v[0:1], s[0:1], v4, s33, v[0:1]
	global_load_dwordx4 v[4:7], v[2:3], off
	s_nop 0
	global_load_dwordx4 v[0:3], v[0:1], off
	v_ashrrev_i32_e32 v53, 31, v52
	v_cmp_ne_u32_e64 s[0:1], 1, v56
	s_andn2_b64 vcc, exec, s[68:69]
	v_lshl_add_u64 v[52:53], v[52:53], 2, s[10:11]
	s_cbranch_vccnz .LBB0_35
	s_waitcnt vmcnt(7)
	v_pk_mul_f32 v[28:29], v[28:29], v[80:81] op_sel_hi:[1,0]
	v_pk_mul_f32 v[30:31], v[30:31], v[80:81] op_sel_hi:[1,0]
.LBB0_35:
	v_lshlrev_b32_e32 v32, 2, v74
	v_mul_lo_u32 v73, v73, s75
	v_add_u32_e32 v32, v32, v73
	s_and_b64 vcc, exec, s[0:1]
	s_waitcnt vmcnt(7)
	ds_write_b128 v32, v[28:31]
	s_cbranch_vccnz .LBB0_37
	s_waitcnt vmcnt(6)
	v_pk_mul_f32 v[24:25], v[24:25], v[82:83] op_sel_hi:[1,0]
	v_pk_mul_f32 v[26:27], v[26:27], v[82:83] op_sel_hi:[1,0]
.LBB0_37:
	s_and_b64 vcc, exec, s[0:1]
	s_waitcnt vmcnt(6)
	ds_write_b128 v32, v[24:27] offset:8320
	s_cbranch_vccnz .LBB0_39
	s_waitcnt vmcnt(5)
	v_pk_mul_f32 v[20:21], v[20:21], v[84:85] op_sel_hi:[1,0]
	v_pk_mul_f32 v[22:23], v[22:23], v[84:85] op_sel_hi:[1,0]
.LBB0_39:
	s_and_b64 vcc, exec, s[0:1]
	s_waitcnt vmcnt(5)
	ds_write_b128 v32, v[20:23] offset:16640
	s_cbranch_vccnz .LBB0_41
	s_waitcnt vmcnt(4)
	v_pk_mul_f32 v[16:17], v[16:17], v[86:87] op_sel_hi:[1,0]
	v_pk_mul_f32 v[18:19], v[18:19], v[86:87] op_sel_hi:[1,0]
.LBB0_41:
	s_and_b64 vcc, exec, s[0:1]
	s_waitcnt vmcnt(4)
	ds_write_b128 v32, v[16:19] offset:24960
	s_cbranch_vccnz .LBB0_43
	s_waitcnt vmcnt(3)
	v_pk_mul_f32 v[12:13], v[12:13], v[88:89] op_sel_hi:[1,0]
	v_pk_mul_f32 v[14:15], v[14:15], v[88:89] op_sel_hi:[1,0]
.LBB0_43:
	s_and_b64 vcc, exec, s[0:1]
	s_waitcnt vmcnt(3)
	ds_write_b128 v32, v[12:15] offset:33280
	s_cbranch_vccnz .LBB0_45
	s_waitcnt vmcnt(2)
	v_pk_mul_f32 v[8:9], v[8:9], v[90:91] op_sel_hi:[1,0]
	v_pk_mul_f32 v[10:11], v[10:11], v[90:91] op_sel_hi:[1,0]
.LBB0_45:
	s_and_b64 vcc, exec, s[0:1]
	s_waitcnt vmcnt(2)
	ds_write_b128 v32, v[8:11] offset:41600
	s_cbranch_vccnz .LBB0_47
	s_waitcnt vmcnt(1)
	v_pk_mul_f32 v[4:5], v[4:5], v[92:93] op_sel_hi:[1,0]
	v_pk_mul_f32 v[6:7], v[6:7], v[92:93] op_sel_hi:[1,0]
.LBB0_47:
	s_and_b64 vcc, exec, s[0:1]
	s_waitcnt vmcnt(1)
	ds_write_b128 v32, v[4:7] offset:49920
	s_cbranch_vccnz .LBB0_49
	s_waitcnt vmcnt(0)
	v_pk_mul_f32 v[0:1], v[0:1], v[94:95] op_sel_hi:[1,0]
	v_pk_mul_f32 v[2:3], v[2:3], v[94:95] op_sel_hi:[1,0]

.LBB0_582:
	s_or_b64 exec, exec, s[6:7]
	s_waitcnt lgkmcnt(0)
	s_barrier
	s_and_saveexec_b64 s[6:7], s[4:5]
	s_cbranch_execz .LBB0_556
	v_div_scale_f32 v5, s[10:11], v4, v4, 1.0
	v_rcp_f32_e32 v6, v5
	v_div_scale_f32 v7, vcc, 1.0, v4, 1.0
	v_readlane_b32 s12, v230, 34
	v_fma_f32 v8, -v5, v6, 1.0
	v_fmac_f32_e32 v6, v8, v6
	v_mul_f32_e32 v8, v7, v6
	v_fma_f32 v9, -v5, v8, v7
	v_fmac_f32_e32 v8, v9, v6
	v_fma_f32 v5, -v5, v8, v7
	v_div_fmas_f32 v5, v5, v6, v8
	v_div_fixup_f32 v80, v5, v4, 1.0
	ds_read2st64_b32 v[14:15], v3 offset1:1
	ds_read2st64_b32 v[88:89], v3 offset0:2 offset1:3
	ds_read2st64_b32 v[94:95], v3 offset0:4 offset1:5
	ds_read2st64_b32 v[92:93], v3 offset0:6 offset1:7
	ds_read2st64_b32 v[100:101], v3 offset0:8 offset1:9
	ds_read2st64_b32 v[102:103], v3 offset0:10 offset1:11
	ds_read2st64_b32 v[104:105], v3 offset0:12 offset1:13
	ds_read2st64_b32 v[106:107], v3 offset0:14 offset1:15
	ds_read2st64_b32 v[108:109], v3 offset0:16 offset1:17
	ds_read2st64_b32 v[110:111], v3 offset0:18 offset1:19
	ds_read2st64_b32 v[112:113], v3 offset0:20 offset1:21
	ds_read2st64_b32 v[114:115], v3 offset0:22 offset1:23
	ds_read2st64_b32 v[116:117], v3 offset0:24 offset1:25
	ds_read2st64_b32 v[118:119], v3 offset0:26 offset1:27
	ds_read2st64_b32 v[120:121], v3 offset0:28 offset1:29
	ds_read2st64_b32 v[122:123], v3 offset0:30 offset1:31
	ds_read2st64_b32 v[124:125], v3 offset0:32 offset1:33
	ds_read2st64_b32 v[126:127], v3 offset0:34 offset1:35
	ds_read2st64_b32 v[128:129], v3 offset0:36 offset1:37
	ds_read2st64_b32 v[130:131], v3 offset0:38 offset1:39
	ds_read2st64_b32 v[132:133], v3 offset0:40 offset1:41
	ds_read2st64_b32 v[134:135], v3 offset0:42 offset1:43
	ds_read2st64_b32 v[136:137], v3 offset0:44 offset1:45
	ds_read2st64_b32 v[138:139], v3 offset0:46 offset1:47
	ds_read2st64_b32 v[140:141], v3 offset0:56 offset1:57
	ds_read2st64_b32 v[142:143], v3 offset0:58 offset1:59
	ds_read2st64_b32 v[4:5], v3 offset0:60 offset1:61
	ds_read2st64_b32 v[8:9], v3 offset0:62 offset1:63
	ds_read2st64_b32 v[146:147], v3 offset0:48 offset1:49
	ds_read2st64_b32 v[174:175], v3 offset0:50 offset1:51
	ds_read2st64_b32 v[176:177], v3 offset0:52 offset1:53
	ds_read2st64_b32 v[178:179], v3 offset0:54 offset1:55
	s_add_i32 s79, s79, s60
	v_and_b32_e32 v3, 31, v2
	v_ashrrev_i32_e32 v2, 3, v2
	v_readlane_b32 s13, v230, 35
	s_waitcnt lgkmcnt(5)
	v_pk_fma_f32 v[6:7], v[28:29], v[80:81], v[4:5] op_sel_hi:[1,0,1] neg_lo:[0,0,1] neg_hi:[0,0,1]
	v_or3_b32 v86, v3, s79, v158
	v_and_b32_e32 v2, -4, v2
	v_mov_b64_e32 v[4:5], s[12:13]
	v_ashrrev_i32_e32 v3, 31, v2
	v_mad_u64_u32 v[4:5], s[10:11], v86, s33, v[4:5]
	v_lshl_add_u64 v[4:5], v[4:5], 0, s[22:23]
	v_lshlrev_b64 v[90:91], 1, v[2:3]
	v_lshl_add_u64 v[28:29], v[4:5], 0, v[90:91]
	s_mov_b64 s[10:11], 0x1800
	s_movk_i32 s8, 0x1000
	v_lshl_add_u64 v[12:13], v[28:29], 0, s[10:11]
	v_add_co_u32_e32 v28, vcc, s8, v28
	v_pk_fma_f32 v[182:183], v[64:65], v[80:81], v[14:15] op_sel_hi:[1,0,1] neg_lo:[0,0,1] neg_hi:[0,0,1]
	v_lshl_add_u64 v[10:11], v[2:3], 2, s[86:87]
	v_addc_co_u32_e32 v29, vcc, 0, v29, vcc
	v_pk_fma_f32 v[98:99], v[66:67], v[80:81], v[88:89] op_sel_hi:[1,0,1] neg_lo:[0,0,1] neg_hi:[0,0,1]
	v_pk_mul_f32 v[184:185], v[182:183], v[182:183]
	s_waitcnt lgkmcnt(4)
	v_pk_fma_f32 v[8:9], v[30:31], v[80:81], v[8:9] op_sel_hi:[1,0,1] neg_lo:[0,0,1] neg_hi:[0,0,1]
	global_load_dwordx4 v[2:5], v[10:11], off
	global_load_dwordx2 v[96:97], v[28:29], off offset:2048
	v_pk_mul_f32 v[180:181], v[98:99], v[98:99]
	v_pk_fma_f32 v[92:93], v[70:71], v[80:81], v[92:93] op_sel_hi:[1,0,1] neg_lo:[0,0,1] neg_hi:[0,0,1]
	v_pk_fma_f32 v[188:189], v[68:69], v[80:81], v[94:95] op_sel_hi:[1,0,1] neg_lo:[0,0,1] neg_hi:[0,0,1]
	v_pk_fma_f32 v[88:89], v[74:75], v[80:81], v[102:103] op_sel_hi:[1,0,1] neg_lo:[0,0,1] neg_hi:[0,0,1]
	v_pk_fma_f32 v[94:95], v[72:73], v[80:81], v[100:101] op_sel_hi:[1,0,1] neg_lo:[0,0,1] neg_hi:[0,0,1]
	v_pk_fma_f32 v[78:79], v[78:79], v[80:81], v[106:107] op_sel_hi:[1,0,1] neg_lo:[0,0,1] neg_hi:[0,0,1]
	v_pk_fma_f32 v[76:77], v[76:77], v[80:81], v[104:105] op_sel_hi:[1,0,1] neg_lo:[0,0,1] neg_hi:[0,0,1]
	v_pk_fma_f32 v[72:73], v[50:51], v[80:81], v[110:111] op_sel_hi:[1,0,1] neg_lo:[0,0,1] neg_hi:[0,0,1]
	v_pk_fma_f32 v[74:75], v[48:49], v[80:81], v[108:109] op_sel_hi:[1,0,1] neg_lo:[0,0,1] neg_hi:[0,0,1]
	v_pk_fma_f32 v[68:69], v[54:55], v[80:81], v[114:115] op_sel_hi:[1,0,1] neg_lo:[0,0,1] neg_hi:[0,0,1]
	v_pk_fma_f32 v[70:71], v[52:53], v[80:81], v[112:113] op_sel_hi:[1,0,1] neg_lo:[0,0,1] neg_hi:[0,0,1]
	v_pk_fma_f32 v[64:65], v[58:59], v[80:81], v[118:119] op_sel_hi:[1,0,1] neg_lo:[0,0,1] neg_hi:[0,0,1]
	v_pk_fma_f32 v[66:67], v[56:57], v[80:81], v[116:117] op_sel_hi:[1,0,1] neg_lo:[0,0,1] neg_hi:[0,0,1]
	v_pk_fma_f32 v[56:57], v[62:63], v[80:81], v[122:123] op_sel_hi:[1,0,1] neg_lo:[0,0,1] neg_hi:[0,0,1]
	v_pk_fma_f32 v[58:59], v[60:61], v[80:81], v[120:121] op_sel_hi:[1,0,1] neg_lo:[0,0,1] neg_hi:[0,0,1]
	v_pk_fma_f32 v[52:53], v[34:35], v[80:81], v[126:127] op_sel_hi:[1,0,1] neg_lo:[0,0,1] neg_hi:[0,0,1]
	v_pk_fma_f32 v[54:55], v[32:33], v[80:81], v[124:125] op_sel_hi:[1,0,1] neg_lo:[0,0,1] neg_hi:[0,0,1]
	v_pk_fma_f32 v[48:49], v[38:39], v[80:81], v[130:131] op_sel_hi:[1,0,1] neg_lo:[0,0,1] neg_hi:[0,0,1]
	v_pk_fma_f32 v[50:51], v[36:37], v[80:81], v[128:129] op_sel_hi:[1,0,1] neg_lo:[0,0,1] neg_hi:[0,0,1]
	v_pk_fma_f32 v[36:37], v[42:43], v[80:81], v[134:135] op_sel_hi:[1,0,1] neg_lo:[0,0,1] neg_hi:[0,0,1]
	v_pk_fma_f32 v[38:39], v[40:41], v[80:81], v[132:133] op_sel_hi:[1,0,1] neg_lo:[0,0,1] neg_hi:[0,0,1]
	v_pk_fma_f32 v[32:33], v[46:47], v[80:81], v[138:139] op_sel_hi:[1,0,1] neg_lo:[0,0,1] neg_hi:[0,0,1]
	v_pk_fma_f32 v[34:35], v[44:45], v[80:81], v[136:137] op_sel_hi:[1,0,1] neg_lo:[0,0,1] neg_hi:[0,0,1]
	s_waitcnt lgkmcnt(2)
	v_pk_fma_f32 v[28:29], v[18:19], v[80:81], v[174:175] op_sel_hi:[1,0,1] neg_lo:[0,0,1] neg_hi:[0,0,1]
	v_pk_fma_f32 v[30:31], v[16:17], v[80:81], v[146:147] op_sel_hi:[1,0,1] neg_lo:[0,0,1] neg_hi:[0,0,1]
	s_waitcnt lgkmcnt(0)
	v_pk_fma_f32 v[18:19], v[22:23], v[80:81], v[178:179] op_sel_hi:[1,0,1] neg_lo:[0,0,1] neg_hi:[0,0,1]
	v_pk_fma_f32 v[22:23], v[20:21], v[80:81], v[176:177] op_sel_hi:[1,0,1] neg_lo:[0,0,1] neg_hi:[0,0,1]
	v_pk_fma_f32 v[14:15], v[26:27], v[80:81], v[142:143] op_sel_hi:[1,0,1] neg_lo:[0,0,1] neg_hi:[0,0,1]
	v_pk_fma_f32 v[16:17], v[24:25], v[80:81], v[140:141] op_sel_hi:[1,0,1] neg_lo:[0,0,1] neg_hi:[0,0,1]
	v_add_f32_e32 v80, v184, v185
	v_add_f32_e32 v80, v80, v180
	v_pk_mul_f32 v[190:191], v[188:189], v[188:189]
	v_add_f32_e32 v80, v80, v181
	v_add_f32_e32 v80, v80, v190
	v_pk_mul_f32 v[186:187], v[92:93], v[92:93]
	v_add_f32_e32 v80, v80, v191
	v_add_f32_e32 v80, v80, v186
	v_pk_mul_f32 v[100:101], v[94:95], v[94:95]
	v_add_f32_e32 v80, v80, v187
	v_add_f32_e32 v80, v80, v100
	v_pk_mul_f32 v[102:103], v[88:89], v[88:89]
	v_add_f32_e32 v80, v80, v101
	v_add_f32_e32 v80, v80, v102
	v_pk_mul_f32 v[104:105], v[76:77], v[76:77]
	v_add_f32_e32 v80, v80, v103
	v_add_f32_e32 v80, v80, v104
	v_pk_mul_f32 v[106:107], v[78:79], v[78:79]
	v_add_f32_e32 v80, v80, v105
	v_add_f32_e32 v80, v80, v106
	v_pk_mul_f32 v[108:109], v[74:75], v[74:75]
	v_add_f32_e32 v80, v80, v107
	v_add_f32_e32 v80, v80, v108
	v_pk_mul_f32 v[110:111], v[72:73], v[72:73]
	v_add_f32_e32 v80, v80, v109
	v_add_f32_e32 v80, v80, v110
	v_pk_mul_f32 v[112:113], v[70:71], v[70:71]
	v_add_f32_e32 v80, v80, v111
	v_add_f32_e32 v80, v80, v112
	v_pk_mul_f32 v[114:115], v[68:69], v[68:69]
	v_add_f32_e32 v80, v80, v113
	v_add_f32_e32 v80, v80, v114
	v_pk_mul_f32 v[116:117], v[66:67], v[66:67]
	v_add_f32_e32 v80, v80, v115
	v_add_f32_e32 v80, v80, v116
	v_pk_mul_f32 v[118:119], v[64:65], v[64:65]
	v_add_f32_e32 v80, v80, v117
	v_add_f32_e32 v80, v80, v118
	v_pk_mul_f32 v[60:61], v[58:59], v[58:59]
	v_add_f32_e32 v80, v80, v119
	v_add_f32_e32 v60, v80, v60
	v_pk_mul_f32 v[62:63], v[56:57], v[56:57]
	v_add_f32_e32 v60, v60, v61
	v_add_f32_e32 v60, v60, v62
	v_pk_mul_f32 v[122:123], v[54:55], v[54:55]
	v_add_f32_e32 v60, v60, v63
	v_add_f32_e32 v60, v60, v122
	v_pk_mul_f32 v[120:121], v[52:53], v[52:53]
	v_add_f32_e32 v60, v60, v123
	v_add_f32_e32 v60, v60, v120
	v_pk_mul_f32 v[126:127], v[50:51], v[50:51]
	v_add_f32_e32 v60, v60, v121
	v_add_f32_e32 v60, v60, v126
	v_pk_mul_f32 v[124:125], v[48:49], v[48:49]
	v_add_f32_e32 v60, v60, v127
	v_add_f32_e32 v60, v60, v124
	v_pk_mul_f32 v[40:41], v[38:39], v[38:39]
	v_add_f32_e32 v60, v60, v125
	v_add_f32_e32 v40, v60, v40
	v_pk_mul_f32 v[42:43], v[36:37], v[36:37]
	v_add_f32_e32 v40, v40, v41
	v_add_f32_e32 v40, v40, v42
	v_pk_mul_f32 v[44:45], v[34:35], v[34:35]
	v_add_f32_e32 v40, v40, v43
	v_add_f32_e32 v40, v40, v44
	v_pk_mul_f32 v[46:47], v[32:33], v[32:33]
	v_add_f32_e32 v40, v40, v45
	v_add_f32_e32 v40, v40, v46
	v_pk_mul_f32 v[130:131], v[30:31], v[30:31]
	v_add_f32_e32 v40, v40, v47
	v_add_f32_e32 v40, v40, v130
	v_pk_mul_f32 v[128:129], v[28:29], v[28:29]
	v_add_f32_e32 v40, v40, v131
	v_add_f32_e32 v40, v40, v128
	v_pk_mul_f32 v[20:21], v[22:23], v[22:23]
	v_add_f32_e32 v40, v40, v129
	v_add_f32_e32 v20, v40, v20
	v_pk_mul_f32 v[132:133], v[18:19], v[18:19]
	v_add_f32_e32 v20, v20, v21
	v_add_f32_e32 v20, v20, v132
	v_pk_mul_f32 v[24:25], v[16:17], v[16:17]
	v_add_f32_e32 v20, v20, v133
	v_add_f32_e32 v20, v20, v24
	v_pk_mul_f32 v[26:27], v[14:15], v[14:15]
	v_add_f32_e32 v20, v20, v25
	v_add_f32_e32 v20, v20, v26
	v_pk_mul_f32 v[82:83], v[6:7], v[6:7]
	v_add_f32_e32 v20, v20, v27
	v_add_f32_e32 v20, v20, v82
	v_pk_mul_f32 v[84:85], v[8:9], v[8:9]
	v_add_f32_e32 v20, v20, v83
	v_add_f32_e32 v20, v20, v84
	v_add_f32_e32 v24, v20, v85
	global_load_dwordx2 v[204:205], v[12:13], off offset:16
	global_load_dwordx4 v[100:103], v[10:11], off offset:32
	global_load_dwordx2 v[206:207], v[12:13], off offset:32
	global_load_dwordx4 v[104:107], v[10:11], off offset:64
	global_load_dwordx2 v[208:209], v[12:13], off offset:48
	global_load_dwordx4 v[108:111], v[10:11], off offset:96
	global_load_dwordx2 v[210:211], v[12:13], off offset:64
	global_load_dwordx4 v[112:115], v[10:11], off offset:128
	global_load_dwordx2 v[212:213], v[12:13], off offset:80
	global_load_dwordx4 v[116:119], v[10:11], off offset:160
	global_load_dwordx2 v[214:215], v[12:13], off offset:96
	global_load_dwordx4 v[120:123], v[10:11], off offset:192
	global_load_dwordx2 v[216:217], v[12:13], off offset:112
	global_load_dwordx4 v[124:127], v[10:11], off offset:224
	global_load_dwordx2 v[218:219], v[12:13], off offset:128
	global_load_dwordx4 v[128:131], v[10:11], off offset:256
	global_load_dwordx2 v[220:221], v[12:13], off offset:144
	global_load_dwordx4 v[132:135], v[10:11], off offset:288
	global_load_dwordx2 v[222:223], v[12:13], off offset:160
	global_load_dwordx4 v[136:139], v[10:11], off offset:320
	global_load_dwordx2 v[224:225], v[12:13], off offset:176
	global_load_dwordx4 v[140:143], v[10:11], off offset:352
	global_load_dwordx2 v[226:227], v[12:13], off offset:192
	global_load_dwordx4 v[232:235], v[10:11], off offset:384
	global_load_dwordx2 v[174:175], v[12:13], off offset:208
	global_load_dwordx4 v[236:239], v[10:11], off offset:416
	global_load_dwordx2 v[176:177], v[12:13], off offset:224
	global_load_dwordx4 v[240:243], v[10:11], off offset:448
	global_load_dwordx2 v[178:179], v[12:13], off offset:240
	global_load_dwordx4 v[244:247], v[10:11], off offset:480
	ds_bpermute_b32 v1, v1, v24
	s_waitcnt vmcnt(30)
	v_lshlrev_b32_e32 v26, 16, v96
	v_and_b32_e32 v27, 0xffff0000, v96
	v_mov_b32_e32 v87, v0
	v_lshlrev_b64 v[20:21], 12, v[86:87]
	s_waitcnt lgkmcnt(0)
	v_add_f32_e32 v1, v24, v1
	v_fmamk_f32 v1, v1, 0x3c000000, v199
	v_mul_f32_e32 v24, 0x4b800000, v1
	v_cmp_gt_f32_e32 vcc, s3, v1
	v_lshlrev_b32_e32 v40, 16, v97
	v_and_b32_e32 v41, 0xffff0000, v97
	v_cndmask_b32_e32 v1, v1, v24, vcc
	v_rsq_f32_e32 v1, v1
	v_lshl_add_u64 v[20:21], s[94:95], 0, v[20:21]
	v_lshl_add_u64 v[20:21], v[20:21], 0, v[90:91]
	v_readlane_b32 s14, v230, 36
	v_mul_f32_e32 v24, 0x45800000, v1
	v_cndmask_b32_e32 v1, v1, v24, vcc
	v_mul_f32_e32 v24, v148, v1
	v_pk_mul_f32 v[42:43], v[182:183], v[24:25] op_sel_hi:[1,0]
	v_pk_mul_f32 v[38:39], v[38:39], v[24:25] op_sel_hi:[1,0]
	v_pk_mul_f32 v[2:3], v[2:3], v[42:43]
	v_pk_mul_f32 v[42:43], v[188:189], v[24:25] op_sel_hi:[1,0]
	v_pk_mul_f32 v[2:3], v[2:3], v[26:27]
	v_pk_mul_f32 v[26:27], v[98:99], v[24:25] op_sel_hi:[1,0]
	v_cvt_pk_bf16_f32 v2, v2, v3
	v_pk_mul_f32 v[4:5], v[4:5], v[26:27]
	v_pk_mul_f32 v[36:37], v[36:37], v[24:25] op_sel_hi:[1,0]
	v_pk_mul_f32 v[4:5], v[4:5], v[40:41]
	v_pk_mul_f32 v[34:35], v[34:35], v[24:25] op_sel_hi:[1,0]
	v_cvt_pk_bf16_f32 v3, v4, v5
	global_store_dwordx2 v[20:21], v[2:3], off
	s_nop 0
	v_pk_mul_f32 v[32:33], v[32:33], v[24:25] op_sel_hi:[1,0]
	v_pk_mul_f32 v[30:31], v[30:31], v[24:25] op_sel_hi:[1,0]
	v_pk_mul_f32 v[28:29], v[28:29], v[24:25] op_sel_hi:[1,0]
	v_pk_mul_f32 v[22:23], v[22:23], v[24:25] op_sel_hi:[1,0]
	v_pk_mul_f32 v[18:19], v[18:19], v[24:25] op_sel_hi:[1,0]
	v_pk_mul_f32 v[16:17], v[16:17], v[24:25] op_sel_hi:[1,0]
	v_pk_mul_f32 v[14:15], v[14:15], v[24:25] op_sel_hi:[1,0]
	v_pk_mul_f32 v[6:7], v[6:7], v[24:25] op_sel_hi:[1,0]
	v_pk_mul_f32 v[8:9], v[8:9], v[24:25] op_sel_hi:[1,0]
	v_readlane_b32 s15, v230, 37
	v_readlane_b32 s16, v230, 38
	v_readlane_b32 s17, v230, 39
	v_readlane_b32 s18, v230, 40
	v_readlane_b32 s19, v230, 41
	s_waitcnt vmcnt(30)
	v_lshlrev_b32_e32 v40, 16, v204
	s_waitcnt vmcnt(29)
	v_pk_mul_f32 v[2:3], v[100:101], v[42:43]
	v_and_b32_e32 v41, 0xffff0000, v204
	v_pk_mul_f32 v[2:3], v[2:3], v[40:41]
	v_pk_mul_f32 v[40:41], v[92:93], v[24:25] op_sel_hi:[1,0]
	v_lshlrev_b32_e32 v26, 16, v205
	v_pk_mul_f32 v[4:5], v[102:103], v[40:41]
	v_and_b32_e32 v27, 0xffff0000, v205
	v_pk_mul_f32 v[4:5], v[4:5], v[26:27]
	v_cvt_pk_bf16_f32 v2, v2, v3
	v_cvt_pk_bf16_f32 v3, v4, v5
	global_store_dwordx2 v[20:21], v[2:3], off offset:16
	s_nop 0
	v_pk_mul_f32 v[40:41], v[94:95], v[24:25] op_sel_hi:[1,0]
	v_pk_mul_f32 v[42:43], v[88:89], v[24:25] op_sel_hi:[1,0]
	s_waitcnt vmcnt(29)
	v_lshlrev_b32_e32 v44, 16, v206
	s_waitcnt vmcnt(28)
	v_pk_mul_f32 v[2:3], v[104:105], v[40:41]
	v_and_b32_e32 v45, 0xffff0000, v206
	v_lshlrev_b32_e32 v26, 16, v207
	v_pk_mul_f32 v[4:5], v[106:107], v[42:43]
	v_and_b32_e32 v27, 0xffff0000, v207
	v_pk_mul_f32 v[2:3], v[2:3], v[44:45]
	v_pk_mul_f32 v[4:5], v[4:5], v[26:27]
	v_cvt_pk_bf16_f32 v2, v2, v3
	v_cvt_pk_bf16_f32 v3, v4, v5
	global_store_dwordx2 v[20:21], v[2:3], off offset:32
	s_nop 0
	v_pk_mul_f32 v[40:41], v[76:77], v[24:25] op_sel_hi:[1,0]
	v_pk_mul_f32 v[42:43], v[78:79], v[24:25] op_sel_hi:[1,0]
	s_waitcnt vmcnt(28)
	v_lshlrev_b32_e32 v44, 16, v208
	s_waitcnt vmcnt(27)
	v_pk_mul_f32 v[2:3], v[40:41], v[108:109]
	v_and_b32_e32 v45, 0xffff0000, v208
	v_lshlrev_b32_e32 v26, 16, v209
	v_pk_mul_f32 v[4:5], v[42:43], v[110:111]
	v_and_b32_e32 v27, 0xffff0000, v209
	v_pk_mul_f32 v[2:3], v[2:3], v[44:45]
	v_pk_mul_f32 v[4:5], v[4:5], v[26:27]
	v_cvt_pk_bf16_f32 v2, v2, v3
	v_cvt_pk_bf16_f32 v3, v4, v5
	global_store_dwordx2 v[20:21], v[2:3], off offset:48
	s_nop 0
	v_pk_mul_f32 v[40:41], v[74:75], v[24:25] op_sel_hi:[1,0]
	v_pk_mul_f32 v[42:43], v[72:73], v[24:25] op_sel_hi:[1,0]
	s_waitcnt vmcnt(27)
	v_lshlrev_b32_e32 v44, 16, v210
	s_waitcnt vmcnt(26)
	v_pk_mul_f32 v[2:3], v[40:41], v[112:113]
	v_and_b32_e32 v45, 0xffff0000, v210
	v_lshlrev_b32_e32 v26, 16, v211
	v_pk_mul_f32 v[4:5], v[42:43], v[114:115]
	v_and_b32_e32 v27, 0xffff0000, v211
	v_pk_mul_f32 v[2:3], v[2:3], v[44:45]
	v_pk_mul_f32 v[4:5], v[4:5], v[26:27]
	v_cvt_pk_bf16_f32 v2, v2, v3
	v_cvt_pk_bf16_f32 v3, v4, v5
	global_store_dwordx2 v[20:21], v[2:3], off offset:64
	s_nop 0
	v_pk_mul_f32 v[40:41], v[70:71], v[24:25] op_sel_hi:[1,0]
	v_pk_mul_f32 v[42:43], v[68:69], v[24:25] op_sel_hi:[1,0]
	s_waitcnt vmcnt(26)
	v_lshlrev_b32_e32 v44, 16, v212
	s_waitcnt vmcnt(25)
	v_pk_mul_f32 v[2:3], v[40:41], v[116:117]
	v_and_b32_e32 v45, 0xffff0000, v212
	v_lshlrev_b32_e32 v26, 16, v213
	v_pk_mul_f32 v[4:5], v[42:43], v[118:119]
	v_and_b32_e32 v27, 0xffff0000, v213
	v_pk_mul_f32 v[2:3], v[2:3], v[44:45]
	v_pk_mul_f32 v[4:5], v[4:5], v[26:27]
	v_cvt_pk_bf16_f32 v2, v2, v3
	v_cvt_pk_bf16_f32 v3, v4, v5
	global_store_dwordx2 v[20:21], v[2:3], off offset:80
	s_nop 0
	v_pk_mul_f32 v[40:41], v[66:67], v[24:25] op_sel_hi:[1,0]
	v_pk_mul_f32 v[42:43], v[64:65], v[24:25] op_sel_hi:[1,0]
	s_waitcnt vmcnt(25)
	v_lshlrev_b32_e32 v44, 16, v214
	s_waitcnt vmcnt(24)
	v_pk_mul_f32 v[2:3], v[40:41], v[120:121]
	v_and_b32_e32 v45, 0xffff0000, v214
	v_lshlrev_b32_e32 v26, 16, v215
	v_pk_mul_f32 v[4:5], v[42:43], v[122:123]
	v_and_b32_e32 v27, 0xffff0000, v215
	v_pk_mul_f32 v[2:3], v[2:3], v[44:45]
	v_pk_mul_f32 v[4:5], v[4:5], v[26:27]
	v_cvt_pk_bf16_f32 v2, v2, v3
	v_cvt_pk_bf16_f32 v3, v4, v5
	global_store_dwordx2 v[20:21], v[2:3], off offset:96
	s_nop 0
	v_pk_mul_f32 v[40:41], v[58:59], v[24:25] op_sel_hi:[1,0]
	v_pk_mul_f32 v[42:43], v[56:57], v[24:25] op_sel_hi:[1,0]
	s_waitcnt vmcnt(24)
	v_lshlrev_b32_e32 v44, 16, v216
	s_waitcnt vmcnt(23)
	v_pk_mul_f32 v[2:3], v[40:41], v[124:125]
	v_and_b32_e32 v45, 0xffff0000, v216
	v_lshlrev_b32_e32 v26, 16, v217
	v_pk_mul_f32 v[4:5], v[42:43], v[126:127]
	v_and_b32_e32 v27, 0xffff0000, v217
	v_pk_mul_f32 v[2:3], v[2:3], v[44:45]
	v_pk_mul_f32 v[4:5], v[4:5], v[26:27]
	v_cvt_pk_bf16_f32 v2, v2, v3
	v_cvt_pk_bf16_f32 v3, v4, v5
	global_store_dwordx2 v[20:21], v[2:3], off offset:112
	s_nop 0
	v_pk_mul_f32 v[40:41], v[54:55], v[24:25] op_sel_hi:[1,0]
	v_pk_mul_f32 v[42:43], v[52:53], v[24:25] op_sel_hi:[1,0]
	s_waitcnt vmcnt(23)
	v_lshlrev_b32_e32 v44, 16, v218
	s_waitcnt vmcnt(22)
	v_pk_mul_f32 v[2:3], v[40:41], v[128:129]
	v_and_b32_e32 v45, 0xffff0000, v218
	v_lshlrev_b32_e32 v26, 16, v219
	v_pk_mul_f32 v[4:5], v[42:43], v[130:131]
	v_and_b32_e32 v27, 0xffff0000, v219
	v_pk_mul_f32 v[2:3], v[2:3], v[44:45]
	v_pk_mul_f32 v[4:5], v[4:5], v[26:27]
	v_cvt_pk_bf16_f32 v2, v2, v3
	v_cvt_pk_bf16_f32 v3, v4, v5
	global_store_dwordx2 v[20:21], v[2:3], off offset:128
	s_nop 0
	v_pk_mul_f32 v[40:41], v[50:51], v[24:25] op_sel_hi:[1,0]
	v_pk_mul_f32 v[42:43], v[48:49], v[24:25] op_sel_hi:[1,0]
	s_waitcnt vmcnt(22)
	v_lshlrev_b32_e32 v44, 16, v220
	s_waitcnt vmcnt(21)
	v_pk_mul_f32 v[2:3], v[40:41], v[132:133]
	v_and_b32_e32 v45, 0xffff0000, v220
	v_lshlrev_b32_e32 v26, 16, v221
	v_pk_mul_f32 v[4:5], v[42:43], v[134:135]
	v_and_b32_e32 v27, 0xffff0000, v221
	v_pk_mul_f32 v[2:3], v[2:3], v[44:45]
	v_pk_mul_f32 v[4:5], v[4:5], v[26:27]
	v_cvt_pk_bf16_f32 v2, v2, v3
	v_cvt_pk_bf16_f32 v3, v4, v5
	global_store_dwordx2 v[20:21], v[2:3], off offset:144
	s_nop 0
	s_waitcnt vmcnt(21)
	v_lshlrev_b32_e32 v40, 16, v222
	s_waitcnt vmcnt(20)
	v_pk_mul_f32 v[2:3], v[38:39], v[136:137]
	v_and_b32_e32 v41, 0xffff0000, v222
	v_lshlrev_b32_e32 v26, 16, v223
	v_pk_mul_f32 v[4:5], v[36:37], v[138:139]
	v_and_b32_e32 v27, 0xffff0000, v223
	v_pk_mul_f32 v[2:3], v[2:3], v[40:41]
	v_pk_mul_f32 v[4:5], v[4:5], v[26:27]
	v_cvt_pk_bf16_f32 v2, v2, v3
	v_cvt_pk_bf16_f32 v3, v4, v5
	global_store_dwordx2 v[20:21], v[2:3], off offset:160
	s_nop 0
	s_waitcnt vmcnt(20)
	v_lshlrev_b32_e32 v36, 16, v224
	s_waitcnt vmcnt(19)
	v_pk_mul_f32 v[2:3], v[34:35], v[140:141]
	v_and_b32_e32 v37, 0xffff0000, v224
	v_lshlrev_b32_e32 v26, 16, v225
	v_pk_mul_f32 v[4:5], v[32:33], v[142:143]
	v_and_b32_e32 v27, 0xffff0000, v225
	v_pk_mul_f32 v[2:3], v[2:3], v[36:37]
	v_pk_mul_f32 v[4:5], v[4:5], v[26:27]
	v_cvt_pk_bf16_f32 v2, v2, v3
	v_cvt_pk_bf16_f32 v3, v4, v5
	global_store_dwordx2 v[20:21], v[2:3], off offset:176
	s_nop 0
	s_waitcnt vmcnt(19)
	v_lshlrev_b32_e32 v32, 16, v226
	s_waitcnt vmcnt(18)
	v_pk_mul_f32 v[2:3], v[30:31], v[232:233]
	v_and_b32_e32 v33, 0xffff0000, v226
	v_lshlrev_b32_e32 v26, 16, v227
	v_pk_mul_f32 v[4:5], v[28:29], v[234:235]
	v_and_b32_e32 v27, 0xffff0000, v227
	v_pk_mul_f32 v[2:3], v[2:3], v[32:33]
	v_pk_mul_f32 v[4:5], v[4:5], v[26:27]
	v_cvt_pk_bf16_f32 v2, v2, v3
	v_cvt_pk_bf16_f32 v3, v4, v5
	global_store_dwordx2 v[20:21], v[2:3], off offset:192
	s_nop 0
	s_waitcnt vmcnt(18)
	v_lshlrev_b32_e32 v28, 16, v174
	s_waitcnt vmcnt(17)
	v_pk_mul_f32 v[2:3], v[22:23], v[236:237]
	v_and_b32_e32 v29, 0xffff0000, v174
	v_lshlrev_b32_e32 v22, 16, v175
	v_pk_mul_f32 v[4:5], v[18:19], v[238:239]
	v_and_b32_e32 v23, 0xffff0000, v175
	v_pk_mul_f32 v[2:3], v[2:3], v[28:29]
	v_pk_mul_f32 v[4:5], v[4:5], v[22:23]
	v_cvt_pk_bf16_f32 v2, v2, v3
	v_cvt_pk_bf16_f32 v3, v4, v5
	global_store_dwordx2 v[20:21], v[2:3], off offset:208
	s_nop 0
	s_waitcnt vmcnt(17)
	v_lshlrev_b32_e32 v22, 16, v176
	s_waitcnt vmcnt(16)
	v_pk_mul_f32 v[2:3], v[16:17], v[240:241]
	v_and_b32_e32 v23, 0xffff0000, v176
	v_lshlrev_b32_e32 v16, 16, v177
	v_pk_mul_f32 v[4:5], v[14:15], v[242:243]
	v_and_b32_e32 v17, 0xffff0000, v177
	v_pk_mul_f32 v[2:3], v[2:3], v[22:23]
	v_pk_mul_f32 v[4:5], v[4:5], v[16:17]
	v_cvt_pk_bf16_f32 v2, v2, v3
	v_cvt_pk_bf16_f32 v3, v4, v5
	global_store_dwordx2 v[20:21], v[2:3], off offset:224
	s_nop 0
	s_waitcnt vmcnt(16)
	v_lshlrev_b32_e32 v10, 16, v178
	v_and_b32_e32 v11, 0xffff0000, v178
	s_waitcnt vmcnt(15)
	v_pk_mul_f32 v[2:3], v[6:7], v[244:245]
	v_lshlrev_b32_e32 v6, 16, v179
	v_and_b32_e32 v7, 0xffff0000, v179
	v_pk_mul_f32 v[4:5], v[8:9], v[246:247]
	v_pk_mul_f32 v[2:3], v[2:3], v[10:11]
	v_pk_mul_f32 v[4:5], v[4:5], v[6:7]
	v_cvt_pk_bf16_f32 v2, v2, v3
	v_cvt_pk_bf16_f32 v3, v4, v5
	global_store_dwordx2 v[20:21], v[2:3], off offset:240
	s_branch .LBB0_556

.LBB0_945:
	v_mov_b32_e32 v1, v194
	v_mov_b32_e32 v7, v0
	v_ashrrev_i32_e32 v1, 6, v1
	v_add_u32_e32 v22, s2, v1
	v_mov_b32_e32 v1, v194
	v_ashrrev_i32_e32 v23, 31, v22
	v_and_b32_e32 v1, 63, v1
	s_waitcnt lgkmcnt(0)
	v_lshlrev_b64 v[2:3], 12, v[22:23]
	v_lshl_add_u64 v[4:5], s[98:99], 0, v[2:3]
	v_lshlrev_b32_e32 v6, 4, v1
	v_lshl_add_u64 v[4:5], v[4:5], 0, v[6:7]
	global_load_dwordx4 v[14:17], v[4:5], off
	global_load_dwordx4 v[18:21], v[4:5], off offset:1024
	global_load_dwordx4 v[26:29], v[4:5], off offset:2048
	global_load_dwordx4 v[42:45], v[4:5], off offset:3072
	v_and_b32_e32 v4, 64, v203
	v_readlane_b32 s0, v230, 1
	v_xor_b32_e32 v5, 32, v203
	v_add_u32_e32 v100, 64, v4
	v_lshlrev_b32_e32 v54, 5, v1
	v_readlane_b32 s1, v230, 2
	v_cmp_lt_i32_e32 vcc, v5, v100
	global_load_dwordx4 v[64:67], v54, s[4:5] offset:16
	global_load_dwordx4 v[68:71], v54, s[4:5]
	v_lshl_add_u64 v[2:3], s[0:1], 0, v[2:3]
	v_cndmask_b32_e32 v4, v203, v5, vcc
	v_lshl_add_u64 v[24:25], v[2:3], 0, v[6:7]
	v_lshlrev_b32_e32 v58, 2, v4
	global_load_dwordx4 v[72:75], v[24:25], off
	global_load_dwordx4 v[10:13], v[24:25], off offset:1024
	global_load_dwordx4 v[6:9], v[24:25], off offset:2048
	global_load_dwordx4 v[2:5], v[24:25], off offset:3072
	v_add_u32_e32 v101, 0x1000, v54
	global_load_dwordx4 v[104:107], v54, s[4:5] offset:2048
	global_load_dwordx4 v[108:111], v54, s[4:5] offset:2064
	global_load_dwordx4 v[112:115], v101, s[4:5]
	global_load_dwordx4 v[116:119], v101, s[4:5] offset:16
	global_load_dwordx4 v[120:123], v101, s[4:5] offset:2048
	global_load_dwordx4 v[124:127], v101, s[4:5] offset:2064
	v_xor_b32_e32 v55, 16, v203
	v_cmp_lt_i32_e32 vcc, v55, v100
	v_xor_b32_e32 v98, 8, v203
	v_xor_b32_e32 v99, 4, v203
	s_mov_b64 s[50:51], -1
	s_waitcnt vmcnt(15)
	v_lshlrev_b32_e32 v56, 16, v14
	v_and_b32_e32 v57, 0xffff0000, v14
	v_lshlrev_b32_e32 v14, 16, v15
	v_and_b32_e32 v15, 0xffff0000, v15
	v_pk_mul_f32 v[96:97], v[56:57], v[56:57]
	v_pk_mul_f32 v[94:95], v[14:15], v[14:15]
	v_add_f32_e32 v59, v96, v97
	v_lshlrev_b32_e32 v76, 16, v16
	v_and_b32_e32 v77, 0xffff0000, v16
	v_add_f32_e32 v59, v59, v94
	v_pk_mul_f32 v[92:93], v[76:77], v[76:77]
	v_add_f32_e32 v59, v95, v59
	v_lshlrev_b32_e32 v16, 16, v17
	v_and_b32_e32 v17, 0xffff0000, v17
	v_add_f32_e32 v59, v92, v59
	v_pk_mul_f32 v[90:91], v[16:17], v[16:17]
	v_add_f32_e32 v59, v93, v59
	s_waitcnt vmcnt(14)
	v_lshlrev_b32_e32 v48, 16, v18
	v_and_b32_e32 v49, 0xffff0000, v18
	v_add_f32_e32 v59, v90, v59
	v_lshlrev_b32_e32 v46, 16, v19
	v_and_b32_e32 v47, 0xffff0000, v19
	v_pk_mul_f32 v[18:19], v[48:49], v[48:49]
	v_add_f32_e32 v59, v91, v59
	v_add_f32_e32 v18, v59, v18
	v_lshlrev_b32_e32 v52, 16, v20
	v_and_b32_e32 v53, 0xffff0000, v20
	v_lshlrev_b32_e32 v50, 16, v21
	v_and_b32_e32 v51, 0xffff0000, v21
	v_pk_mul_f32 v[20:21], v[46:47], v[46:47]
	v_add_f32_e32 v18, v19, v18
	v_add_f32_e32 v18, v20, v18
	s_waitcnt vmcnt(13)
	v_lshlrev_b32_e32 v36, 16, v26
	v_and_b32_e32 v37, 0xffff0000, v26
	v_lshlrev_b32_e32 v34, 16, v27
	v_and_b32_e32 v35, 0xffff0000, v27
	v_lshlrev_b32_e32 v40, 16, v28
	v_and_b32_e32 v41, 0xffff0000, v28
	v_lshlrev_b32_e32 v38, 16, v29
	v_and_b32_e32 v39, 0xffff0000, v29
	s_waitcnt vmcnt(12)
	v_lshlrev_b32_e32 v28, 16, v42
	v_and_b32_e32 v29, 0xffff0000, v42
	v_lshlrev_b32_e32 v26, 16, v43
	v_and_b32_e32 v27, 0xffff0000, v43
	v_pk_mul_f32 v[42:43], v[52:53], v[52:53]
	v_add_f32_e32 v18, v21, v18
	v_add_f32_e32 v18, v42, v18
	v_lshlrev_b32_e32 v32, 16, v44
	v_and_b32_e32 v33, 0xffff0000, v44
	v_lshlrev_b32_e32 v30, 16, v45
	v_and_b32_e32 v31, 0xffff0000, v45
	v_pk_mul_f32 v[44:45], v[50:51], v[50:51]
	v_add_f32_e32 v18, v43, v18
	v_add_f32_e32 v18, v44, v18
	v_pk_mul_f32 v[60:61], v[36:37], v[36:37]
	v_add_f32_e32 v18, v45, v18
	v_add_f32_e32 v18, v18, v60
	v_pk_mul_f32 v[62:63], v[34:35], v[34:35]
	v_add_f32_e32 v18, v61, v18
	v_add_f32_e32 v18, v62, v18
	v_pk_mul_f32 v[78:79], v[40:41], v[40:41]
	v_add_f32_e32 v18, v63, v18
	v_add_f32_e32 v18, v78, v18
	v_pk_mul_f32 v[80:81], v[38:39], v[38:39]
	v_add_f32_e32 v18, v79, v18
	v_add_f32_e32 v18, v80, v18
	v_pk_mul_f32 v[82:83], v[28:29], v[28:29]
	v_add_f32_e32 v18, v81, v18
	v_add_f32_e32 v18, v18, v82
	v_pk_mul_f32 v[84:85], v[26:27], v[26:27]
	v_add_f32_e32 v18, v83, v18
	v_add_f32_e32 v18, v84, v18
	v_pk_mul_f32 v[86:87], v[32:33], v[32:33]
	v_add_f32_e32 v18, v85, v18
	v_add_f32_e32 v18, v86, v18
	v_pk_mul_f32 v[88:89], v[30:31], v[30:31]
	v_add_f32_e32 v18, v87, v18
	v_add_f32_e32 v18, v88, v18
	v_add_f32_e32 v18, v89, v18
	ds_bpermute_b32 v19, v58, v18
	v_cndmask_b32_e32 v21, v203, v55, vcc
	v_lshlrev_b32_e32 v59, 2, v21
	v_cmp_lt_i32_e32 vcc, v98, v100
	v_xor_b32_e32 v20, 2, v203
	s_waitcnt lgkmcnt(0)
	v_add_f32_e32 v18, v18, v19
	ds_bpermute_b32 v19, v59, v18
	v_cndmask_b32_e32 v42, v203, v98, vcc
	v_lshlrev_b32_e32 v60, 2, v42
	v_cmp_lt_i32_e32 vcc, v99, v100
	v_xor_b32_e32 v21, 1, v203
	s_waitcnt lgkmcnt(0)
	v_add_f32_e32 v18, v18, v19
	ds_bpermute_b32 v19, v60, v18
	v_cndmask_b32_e32 v43, v203, v99, vcc
	v_lshlrev_b32_e32 v61, 2, v43
	v_cmp_lt_i32_e32 vcc, v20, v100
	v_cndmask_b32_e64 v42, 0, 1, s[6:7]
	s_waitcnt lgkmcnt(0)
	v_add_f32_e32 v18, v18, v19
	ds_bpermute_b32 v19, v61, v18
	v_cndmask_b32_e32 v20, v203, v20, vcc
	v_lshlrev_b32_e32 v62, 2, v20
	v_cmp_lt_i32_e32 vcc, v21, v100
	v_cmp_ne_u32_e64 s[0:1], 1, v42
	s_waitcnt lgkmcnt(0)
	v_add_f32_e32 v19, v18, v19
	ds_bpermute_b32 v20, v62, v19
	v_cndmask_b32_e32 v18, v203, v21, vcc
	v_lshlrev_b32_e32 v63, 2, v18
	s_waitcnt vmcnt(9)
	v_lshlrev_b32_e32 v18, 16, v72
	v_and_b32_e32 v21, 0xffff0000, v73
	s_waitcnt lgkmcnt(0)
	v_add_f32_e32 v42, v19, v20
	ds_bpermute_b32 v43, v63, v42
	v_and_b32_e32 v19, 0xffff0000, v72
	v_lshlrev_b32_e32 v20, 16, v73
	v_lshlrev_b32_e32 v44, 16, v74
	v_and_b32_e32 v45, 0xffff0000, v74
	s_waitcnt lgkmcnt(0)
	v_add_f32_e32 v42, v42, v43
	v_fmamk_f32 v42, v42, 0x3a000000, v199
	v_mul_f32_e32 v43, 0x4b800000, v42
	v_cmp_gt_f32_e32 vcc, s3, v42
	v_lshlrev_b32_e32 v72, 16, v75
	v_and_b32_e32 v73, 0xffff0000, v75
	v_cndmask_b32_e32 v42, v42, v43, vcc
	v_rsq_f32_e32 v42, v42
	s_nop 0
	v_mul_f32_e32 v43, 0x45800000, v42
	v_cndmask_b32_e32 v42, v42, v43, vcc
	v_pk_mul_f32 v[56:57], v[42:43], v[56:57] op_sel_hi:[0,1]
	v_pk_mul_f32 v[74:75], v[42:43], v[76:77] op_sel_hi:[0,1]
	v_pk_mul_f32 v[76:77], v[42:43], v[14:15] op_sel_hi:[0,1]
	v_pk_mul_f32 v[16:17], v[42:43], v[16:17] op_sel_hi:[0,1]
	v_pk_fma_f32 v[18:19], v[68:69], v[56:57], v[18:19]
	v_pk_fma_f32 v[14:15], v[64:65], v[74:75], v[44:45]
	v_pk_fma_f32 v[20:21], v[70:71], v[76:77], v[20:21]
	v_pk_fma_f32 v[16:17], v[66:67], v[16:17], v[72:73]
	s_andn2_b64 vcc, exec, s[6:7]
	s_cbranch_vccnz .LBB0_947
	v_pk_mul_f32 v[44:45], v[18:19], v[18:19]
	v_pk_mul_f32 v[56:57], v[20:21], v[20:21]
	v_add_f32_e32 v43, v44, v45
	v_add_f32_e32 v43, v56, v43
	v_pk_mul_f32 v[64:65], v[14:15], v[14:15]
	v_add_f32_e32 v43, v57, v43
	v_add_f32_e32 v43, v64, v43
	v_pk_mul_f32 v[66:67], v[16:17], v[16:17]
	v_add_f32_e32 v43, v65, v43
	v_add_f32_e32 v43, v66, v43
	v_add_f32_e32 v65, v67, v43
	v_cvt_pk_bf16_f32 v66, v18, v19
	v_cvt_pk_bf16_f32 v67, v20, v21
	v_cvt_pk_bf16_f32 v68, v14, v15
	v_cvt_pk_bf16_f32 v69, v16, v17
	s_mov_b64 s[50:51], 0
	global_store_dwordx4 v[24:25], v[66:69], off

.LBB0_949:
	v_mov_b32_e32 v55, v0
	v_lshl_add_u64 v[18:19], s[4:5], 0, v[54:55]
	s_nop 0
	v_mov_b32_e32 v43, v42
	s_waitcnt vmcnt(9)
	v_lshlrev_b32_e32 v54, 16, v10
	v_and_b32_e32 v55, 0xffff0000, v10
	v_lshlrev_b32_e32 v66, 16, v11
	v_and_b32_e32 v67, 0xffff0000, v11
	v_lshlrev_b32_e32 v10, 16, v12
	v_and_b32_e32 v11, 0xffff0000, v12
	v_lshlrev_b32_e32 v12, 16, v13
	v_and_b32_e32 v13, 0xffff0000, v13
	v_pk_mul_f32 v[48:49], v[42:43], v[48:49]
	v_pk_mul_f32 v[52:53], v[42:43], v[52:53]
	v_pk_mul_f32 v[46:47], v[42:43], v[46:47]
	v_pk_mul_f32 v[50:51], v[42:43], v[50:51]
	s_and_b64 vcc, exec, s[0:1]
	s_mov_b64 s[50:51], -1
	s_waitcnt vmcnt(6)
	v_pk_fma_f32 v[14:15], v[48:49], v[104:105], v[54:55]
	s_waitcnt vmcnt(5)
	v_pk_fma_f32 v[10:11], v[52:53], v[108:109], v[10:11]
	v_pk_fma_f32 v[16:17], v[46:47], v[106:107], v[66:67]
	v_pk_fma_f32 v[12:13], v[50:51], v[110:111], v[12:13]
	s_cbranch_vccnz .LBB0_951
	v_pk_mul_f32 v[18:19], v[14:15], v[14:15]
	v_cvt_pk_bf16_f32 v46, v14, v15
	v_add_f32_e32 v18, v65, v18
	v_add_f32_e32 v20, v19, v18
	v_pk_mul_f32 v[18:19], v[16:17], v[16:17]
	v_cvt_pk_bf16_f32 v47, v16, v17
	v_add_f32_e32 v18, v18, v20
	v_add_f32_e32 v20, v19, v18
	v_pk_mul_f32 v[18:19], v[10:11], v[10:11]
	v_cvt_pk_bf16_f32 v48, v10, v11
	v_add_f32_e32 v18, v18, v20
	v_add_f32_e32 v20, v19, v18
	v_pk_mul_f32 v[18:19], v[12:13], v[12:13]
	v_cvt_pk_bf16_f32 v49, v12, v13
	v_add_f32_e32 v18, v18, v20
	v_add_f32_e32 v18, v19, v18
	s_mov_b64 s[50:51], 0
	global_store_dwordx4 v[24:25], v[46:49], off offset:1024

.LBB0_953:
	s_nop 0
	v_or_b32_e32 v10, 0x400, v64
	v_lshlrev_b32_e32 v14, 2, v10
	v_lshlrev_b32_e32 v16, 16, v6
	v_and_b32_e32 v17, 0xffff0000, v6
	v_lshlrev_b32_e32 v20, 16, v7
	v_and_b32_e32 v21, 0xffff0000, v7
	v_lshlrev_b32_e32 v6, 16, v8
	v_and_b32_e32 v7, 0xffff0000, v8
	v_lshlrev_b32_e32 v8, 16, v9
	v_and_b32_e32 v9, 0xffff0000, v9
	v_pk_mul_f32 v[36:37], v[42:43], v[36:37]
	v_pk_mul_f32 v[40:41], v[42:43], v[40:41]
	v_pk_mul_f32 v[34:35], v[42:43], v[34:35]
	v_pk_mul_f32 v[38:39], v[42:43], v[38:39]
	s_and_b64 vcc, exec, s[0:1]
	s_mov_b64 s[50:51], -1
	s_waitcnt vmcnt(5)
	v_pk_fma_f32 v[10:11], v[36:37], v[112:113], v[16:17]
	s_waitcnt vmcnt(4)
	v_pk_fma_f32 v[6:7], v[40:41], v[116:117], v[6:7]
	v_pk_fma_f32 v[12:13], v[34:35], v[114:115], v[20:21]
	v_pk_fma_f32 v[8:9], v[38:39], v[118:119], v[8:9]
	s_cbranch_vccnz .LBB0_955
	v_pk_mul_f32 v[16:17], v[10:11], v[10:11]
	v_cvt_pk_bf16_f32 v34, v10, v11
	v_add_f32_e32 v15, v18, v16
	v_add_f32_e32 v15, v17, v15
	v_pk_mul_f32 v[16:17], v[12:13], v[12:13]
	v_cvt_pk_bf16_f32 v35, v12, v13
	v_add_f32_e32 v15, v16, v15
	v_add_f32_e32 v15, v17, v15
	v_pk_mul_f32 v[16:17], v[6:7], v[6:7]
	v_cvt_pk_bf16_f32 v36, v6, v7
	v_add_f32_e32 v15, v16, v15
	v_add_f32_e32 v15, v17, v15
	v_pk_mul_f32 v[16:17], v[8:9], v[8:9]
	v_cvt_pk_bf16_f32 v37, v8, v9
	v_add_f32_e32 v15, v16, v15
	v_add_f32_e32 v15, v17, v15
	s_mov_b64 s[50:51], 0
	global_store_dwordx4 v[24:25], v[34:37], off offset:2048

.LBB0_957:
	s_nop 0
	v_or_b32_e32 v6, 0x600, v64
	v_lshlrev_b32_e32 v10, 2, v6
	v_lshlrev_b32_e32 v12, 16, v2
	v_and_b32_e32 v13, 0xffff0000, v2
	v_lshlrev_b32_e32 v20, 16, v3
	v_and_b32_e32 v21, 0xffff0000, v3
	v_lshlrev_b32_e32 v2, 16, v4
	v_and_b32_e32 v3, 0xffff0000, v4
	v_lshlrev_b32_e32 v4, 16, v5
	v_and_b32_e32 v5, 0xffff0000, v5
	v_pk_mul_f32 v[28:29], v[42:43], v[28:29]
	v_pk_mul_f32 v[32:33], v[42:43], v[32:33]
	v_pk_mul_f32 v[26:27], v[42:43], v[26:27]
	v_pk_mul_f32 v[30:31], v[42:43], v[30:31]
	s_and_b64 vcc, exec, s[0:1]
	s_mov_b64 s[50:51], -1
	s_waitcnt vmcnt(4)
	v_pk_fma_f32 v[6:7], v[28:29], v[120:121], v[12:13]
	s_waitcnt vmcnt(3)
	v_pk_fma_f32 v[2:3], v[32:33], v[124:125], v[2:3]
	v_pk_fma_f32 v[8:9], v[26:27], v[122:123], v[20:21]
	v_pk_fma_f32 v[4:5], v[30:31], v[126:127], v[4:5]
	s_cbranch_vccnz .LBB0_960
	v_pk_mul_f32 v[12:13], v[6:7], v[6:7]
	v_cvt_pk_bf16_f32 v16, v6, v7
	v_add_f32_e32 v11, v15, v12
	v_add_f32_e32 v11, v13, v11
	v_pk_mul_f32 v[12:13], v[8:9], v[8:9]
	v_cvt_pk_bf16_f32 v17, v8, v9
	v_add_f32_e32 v11, v12, v11
	v_add_f32_e32 v11, v13, v11
	v_pk_mul_f32 v[12:13], v[2:3], v[2:3]
	v_cvt_pk_bf16_f32 v18, v2, v3
	v_add_f32_e32 v11, v12, v11
	v_add_f32_e32 v11, v13, v11
	v_pk_mul_f32 v[12:13], v[4:5], v[4:5]
	v_cvt_pk_bf16_f32 v19, v4, v5
	v_add_f32_e32 v11, v12, v11
	v_add_f32_e32 v11, v13, v11
	global_store_dwordx4 v[24:25], v[16:19], off offset:3072
	s_cbranch_execz .LBB0_961
